# v074 stack + main attention: loop-invariant Q-fragment LDS addresses (8 VALU adds per tile and wave removed; K adds use a scalar delta)
# baseline (speedup 1.0000x reference)
.LBB0_692:
	s_and_b64 vcc, exec, s[4:5]
	s_cbranch_vccz .LBB0_783
	s_and_b32 s0, s22, 0x7fffffc0
	s_cmpk_lg_i32 s0, 0x1c0
	s_mov_b64 s[4:5], -1
	s_cbranch_scc0 .LBB0_745
	s_cmpk_lt_u32 s22, 0x200
	s_cbranch_scc1 .LBB0_744
	s_add_i32 s0, s22, 0xfffffe00
	v_mbcnt_lo_u32_b32 v0, -1, 0
	v_mbcnt_hi_u32_b32 v0, -1, v0
	s_lshr_b32 s4, s0, 5
	v_add_u32_e32 v36, s93, v0
	s_lshl_b32 s0, s22, 8
	s_lshl_b32 s12, s4, 11
	v_readfirstlane_b32 s2, v36
	s_and_b32 s0, s0, 0x700
	s_ashr_i32 s5, s2, 6
	s_or_b32 s0, s12, s0
	s_lshl_b32 s2, s5, 5
	v_readlane_b32 s8, v255, 11
	v_and_b32_e32 v0, 31, v36
	s_add_i32 s0, s2, s0
	v_readlane_b32 s9, v255, 12
	s_bfe_u32 s1, s22, 0x20003
	v_or_b32_e32 v4, s0, v0
	v_mov_b64_e32 v[2:3], s[8:9]
	v_bfe_u32 v37, v36, 5, 1
	v_mad_i64_i32 v[2:3], s[2:3], v4, s72, v[2:3]
	s_lshl_b32 s36, s1, 8
	v_lshl_add_u64 v[2:3], v[2:3], 0, s[36:37]
	v_lshlrev_b32_e32 v34, 4, v37
	v_mov_b32_e32 v35, v1
	v_lshl_add_u64 v[30:31], v[2:3], 0, v[34:35]
	global_load_dwordx4 v[2:5], v[30:31], off offset:2560
	global_load_dwordx4 v[6:9], v[30:31], off offset:2592
	global_load_dwordx4 v[10:13], v[30:31], off offset:2624
	global_load_dwordx4 v[14:17], v[30:31], off offset:2656
	global_load_dwordx4 v[18:21], v[30:31], off offset:2688
	global_load_dwordx4 v[22:25], v[30:31], off offset:2720
	global_load_dwordx4 v[26:29], v[30:31], off offset:2752
	s_nop 0
	global_load_dwordx4 v[30:33], v[30:31], off offset:2784
	v_lshlrev_b32_e32 v35, 4, v36
	v_and_b32_e32 v42, 0xf0, v35
	s_movk_i32 s6, 0x60
	v_bitop3_b32 v215, v34, v42, s6 bitop3:0x36
	s_movk_i32 s6, 0x80
	v_bitop3_b32 v216, v34, v42, s6 bitop3:0x36
	s_movk_i32 s6, 0xa0
	v_bitop3_b32 v217, v34, v42, s6 bitop3:0x36
	s_movk_i32 s6, 0xc0
	s_lshl_b32 s2, s5, 9
	s_lshl_b32 s3, s5, 13
	v_bitop3_b32 v218, v34, v42, s6 bitop3:0x36
	s_movk_i32 s6, 0xe0
	s_lshl_b32 s13, s4, 8
	v_bfe_u32 v38, v36, 4, 2
	v_bfe_u32 v39, v36, 2, 3
	v_bitop3_b32 v219, v34, v42, s6 bitop3:0x36
	s_lshl_b32 s6, s5, 3
	s_add_i32 s15, s3, 0
	s_add_i32 s14, s2, 0
	s_lshl_b32 s1, s1, 7
	s_add_i32 s13, s13, 0x8000
	v_lshlrev_b32_e32 v41, 3, v36
	v_or_b32_e32 v43, s6, v38
	v_or_b32_e32 v39, s6, v39
	s_add_i32 s15, s15, 0x11000
	s_add_i32 s14, s14, 0x10000
	s_movk_i32 s2, 0xb00
	v_and_b32_e32 v40, 32, v36
	v_lshlrev_b32_e32 v212, 8, v0
	v_bitop3_b32 v0, v37, v36, 15 bitop3:0x78
	v_and_b32_e32 v37, 24, v41
	v_bitop3_b32 v38, s6, v36, v38 bitop3:0x36
	v_mul_lo_u32 v39, v39, s2
	v_mul_lo_u32 v44, v43, s2
	v_bitop3_b32 v43, v43, v36, 4 bitop3:0x36
	s_add_u32 s36, s8, s36
	v_lshlrev_b32_e32 v38, 3, v38
	v_or3_b32 v37, v40, v37, v39
	s_movk_i32 s2, 0x78
	v_lshlrev_b32_e32 v39, 3, v43
	s_addc_u32 s38, s9, 0
	s_mul_i32 s4, s4, 0xb00000
	v_and_or_b32 v38, v38, s2, v44
	v_lshlrev_b32_e32 v196, 1, v37
	v_and_or_b32 v37, v39, s2, v44
	s_mul_hi_u32 s3, s12, 0x1600
	s_add_u32 s2, s36, s4
	v_add_u32_e32 v45, s15, v212
	s_addc_u32 s3, s38, s3
	s_lshl_b32 s6, s5, 11
	v_bitop3_b32 v213, v34, v42, 32 bitop3:0x36
	v_bitop3_b32 v214, v34, v42, 64 bitop3:0x36
	v_lshl_add_u32 v40, v0, 4, v45
	v_lshlrev_b32_e32 v0, 1, v38
	s_add_u32 s4, s2, 0x1200
	v_add_u32_e32 v43, v45, v213
	v_add_u32_e32 v46, v45, v214
	v_add_u32_e32 v47, v45, v215
	v_add_u32_e32 v48, v45, v216
	v_add_u32_e32 v49, v45, v217
	v_add_u32_e32 v50, v45, v218
	v_add_u32_e32 v45, v45, v219
	s_addc_u32 s5, s3, 0
	v_lshl_add_u64 v[52:53], s[2:3], 0, v[0:1]
	s_add_i32 s39, s6, 0
	v_lshl_add_u32 v198, v37, 1, v249
	v_lshl_add_u64 v[52:53], v[52:53], 0, s[26:27]
	s_add_i32 m0, s39, 0x8000
	v_mov_b32_e32 v199, v1
	global_load_lds_dwordx4 v[52:53], off
	s_mov_b32 m0, s39
	v_lshl_add_u64 v[52:53], s[2:3], 0, v[198:199]
	global_load_lds_dwordx4 v196, s[4:5]
	v_lshl_add_u64 v[52:53], v[52:53], 0, s[26:27]
	s_add_i32 m0, s39, 0x8400
	v_or_b32_e32 v200, 0x80, v196
	global_load_lds_dwordx4 v[52:53], off
	s_add_i32 m0, s39, 0x400
	s_nop 0
	global_load_lds_dwordx4 v200, s[4:5]
	s_waitcnt vmcnt(11)
	ds_write_b128 v40, v[2:5]
	s_waitcnt vmcnt(10)
	ds_write_b128 v43, v[6:9]
	s_waitcnt vmcnt(9)
	ds_write_b128 v46, v[10:13]
	s_waitcnt vmcnt(8)
	ds_write_b128 v47, v[14:17]
	s_waitcnt vmcnt(7)
	ds_write_b128 v48, v[18:21]
	s_waitcnt vmcnt(6)
	ds_write_b128 v49, v[22:25]
	s_waitcnt vmcnt(5)
	ds_write_b128 v50, v[26:29]
	s_waitcnt vmcnt(4)
	ds_write_b128 v45, v[30:33]
	v_or_b32_e32 v2, 32, v34
	v_lshlrev_b32_e32 v9, 1, v36
	v_and_b32_e32 v11, 0x118, v41
	v_or_b32_e32 v3, 64, v34
	v_or_b32_e32 v4, 0x60, v34
	v_or_b32_e32 v5, 0x80, v34
	v_or_b32_e32 v6, 0xa0, v34
	v_or_b32_e32 v7, 0xc0, v34
	v_or_b32_e32 v8, 0xe0, v34
	v_and_b32_e32 v10, 0xc0, v35
	s_waitcnt vmcnt(0)
	s_movk_i32 s2, 0xf0
	v_bitop3_b32 v222, v2, v212, v42 bitop3:0xde
	v_and_or_b32 v2, v9, 32, v11
	v_mov_b32_e32 v16, v1
	v_mov_b32_e32 v17, v1
	v_bitop3_b32 v220, v34, v35, s2 bitop3:0x78
	v_bitop3_b32 v221, v34, v212, v42 bitop3:0xde
	v_bitop3_b32 v223, v3, v212, v42 bitop3:0xde
	v_bitop3_b32 v224, v4, v212, v42 bitop3:0xde
	v_bitop3_b32 v225, v5, v212, v42 bitop3:0xde
	v_bitop3_b32 v226, v6, v212, v42 bitop3:0xde
	v_bitop3_b32 v227, v7, v212, v42 bitop3:0xde
	v_bitop3_b32 v228, v8, v212, v42 bitop3:0xde
	v_add_u32_e32 v221, s15, v221
	v_add_u32_e32 v222, s15, v222
	v_add_u32_e32 v223, s15, v223
	v_add_u32_e32 v224, s15, v224
	v_add_u32_e32 v225, s15, v225
	v_add_u32_e32 v226, s15, v226
	v_add_u32_e32 v227, s15, v227
	v_add_u32_e32 v228, s15, v228
	v_add3_u32 v229, v10, 0, v2
	v_mov_b32_e32 v2, v1
	v_mov_b32_e32 v3, v1
	v_mov_b32_e32 v4, v1
	v_mov_b32_e32 v5, v1
	v_mov_b32_e32 v6, v1
	v_mov_b32_e32 v7, v1
	v_mov_b32_e32 v8, v1
	v_mov_b32_e32 v9, v1
	v_mov_b32_e32 v10, v1
	v_mov_b32_e32 v11, v1
	v_mov_b32_e32 v12, v1
	v_mov_b32_e32 v13, v1
	v_mov_b32_e32 v14, v1
	v_mov_b32_e32 v15, v1
	v_mov_b64_e32 v[80:81], v[16:17]
	v_mov_b64_e32 v[48:49], v[16:17]
	v_mov_b64_e32 v[32:33], v[16:17]
	v_mov_b64_e32 v[128:129], v[16:17]
	v_mov_b64_e32 v[112:113], v[16:17]
	v_mov_b64_e32 v[96:97], v[16:17]
	v_mov_b64_e32 v[64:65], v[16:17]
	v_mov_b32_e32 v197, v1
	v_mov_b32_e32 v201, v1
	s_mov_b32 s40, 0
	v_mov_b32_e32 v202, v1
	v_mov_b32_e32 v203, v1
	v_mov_b32_e32 v231, 0
	s_mov_b64 s[4:5], 0
	s_mov_b64 s[6:7], -1
	v_mov_b64_e32 v[78:79], v[14:15]
	v_mov_b64_e32 v[76:77], v[12:13]
	v_mov_b64_e32 v[74:75], v[10:11]
	v_mov_b64_e32 v[72:73], v[8:9]
	v_mov_b64_e32 v[70:71], v[6:7]
	v_mov_b64_e32 v[68:69], v[4:5]
	v_mov_b64_e32 v[66:67], v[2:3]
	v_mov_b64_e32 v[46:47], v[14:15]
	v_mov_b64_e32 v[44:45], v[12:13]
	v_mov_b64_e32 v[42:43], v[10:11]
	v_mov_b64_e32 v[40:41], v[8:9]
	v_mov_b64_e32 v[38:39], v[6:7]
	v_mov_b64_e32 v[36:37], v[4:5]
	v_mov_b64_e32 v[34:35], v[2:3]
	v_mov_b64_e32 v[30:31], v[14:15]
	v_mov_b64_e32 v[28:29], v[12:13]
	v_mov_b64_e32 v[26:27], v[10:11]
	v_mov_b64_e32 v[24:25], v[8:9]
	v_mov_b64_e32 v[22:23], v[6:7]
	v_mov_b64_e32 v[20:21], v[4:5]
	v_mov_b64_e32 v[18:19], v[2:3]
	v_mov_b64_e32 v[126:127], v[14:15]
	v_mov_b64_e32 v[124:125], v[12:13]
	v_mov_b64_e32 v[122:123], v[10:11]
	v_mov_b64_e32 v[120:121], v[8:9]
	v_mov_b64_e32 v[118:119], v[6:7]
	v_mov_b64_e32 v[116:117], v[4:5]
	v_mov_b64_e32 v[114:115], v[2:3]
	v_mov_b64_e32 v[110:111], v[14:15]
	v_mov_b64_e32 v[108:109], v[12:13]
	v_mov_b64_e32 v[106:107], v[10:11]
	v_mov_b64_e32 v[104:105], v[8:9]
	v_mov_b64_e32 v[102:103], v[6:7]
	v_mov_b64_e32 v[100:101], v[4:5]
	v_mov_b64_e32 v[98:99], v[2:3]
	v_mov_b64_e32 v[94:95], v[14:15]
	v_mov_b64_e32 v[92:93], v[12:13]
	v_mov_b64_e32 v[90:91], v[10:11]
	v_mov_b64_e32 v[88:89], v[8:9]
	v_mov_b64_e32 v[86:87], v[6:7]
	v_mov_b64_e32 v[84:85], v[4:5]
	v_mov_b64_e32 v[82:83], v[2:3]
	v_mov_b64_e32 v[62:63], v[14:15]
	v_mov_b64_e32 v[60:61], v[12:13]
	v_mov_b64_e32 v[58:59], v[10:11]
	v_mov_b64_e32 v[56:57], v[8:9]
	v_mov_b64_e32 v[54:55], v[6:7]
	v_mov_b64_e32 v[52:53], v[4:5]
	v_mov_b64_e32 v[50:51], v[2:3]
	v_mov_b32_e32 v230, 0
	s_waitcnt vmcnt(0) lgkmcnt(0)
	s_barrier
	s_branch .LBB0_699

.LBB0_701:
	s_andn2_b64 vcc, exec, s[6:7]
	s_add_i32 s3, s2, 0
	s_sub_i32 s98, s3, s15
	s_cbranch_vccnz .LBB0_710
.LBB0_702:
	v_add_u32_e32 v130, s98, v221
	ds_read_b128 v[130:133], v130 offset:32768
	ds_read_b128 v[134:137], v221
	v_add_u32_e32 v206, s3, v212
	v_add_u32_e32 v138, v206, v220
	v_add_u32_e32 v207, s98, v222
	s_cmp_lg_u32 s40, 0
	s_cselect_b64 s[8:9], -1, 0
	s_cmp_eq_u32 s40, 0
	s_waitcnt lgkmcnt(0)
	v_mfma_f32_32x32x16_bf16 v[146:161], v[130:133], v[134:137], 0
	ds_read_b128 v[130:133], v138 offset:40960
	ds_read_b128 v[208:211], v207 offset:32768
	ds_read_b128 v[232:235], v222
	v_add_u32_e32 v207, v206, v213
	s_waitcnt lgkmcnt(0)
	v_mfma_f32_32x32x16_bf16 v[146:161], v[208:211], v[232:235], v[146:161]
	ds_read_b128 v[208:211], v207 offset:40960
	v_add_u32_e32 v207, s98, v223
	v_mfma_f32_32x32x16_bf16 v[130:145], v[130:133], v[134:137], 0
	s_waitcnt lgkmcnt(0)
	v_mfma_f32_32x32x16_bf16 v[130:145], v[208:211], v[232:235], v[130:145]
	ds_read_b128 v[208:211], v207 offset:32768
	ds_read_b128 v[232:235], v223
	v_add_u32_e32 v207, v206, v214
	s_waitcnt lgkmcnt(0)
	v_mfma_f32_32x32x16_bf16 v[146:161], v[208:211], v[232:235], v[146:161]
	ds_read_b128 v[208:211], v207 offset:40960
	v_add_u32_e32 v207, s98, v224
	s_waitcnt lgkmcnt(0)
	v_mfma_f32_32x32x16_bf16 v[130:145], v[208:211], v[232:235], v[130:145]
	ds_read_b128 v[208:211], v207 offset:32768
	ds_read_b128 v[232:235], v224
	v_add_u32_e32 v207, v206, v215
	s_waitcnt lgkmcnt(0)
	v_mfma_f32_32x32x16_bf16 v[146:161], v[208:211], v[232:235], v[146:161]
	ds_read_b128 v[208:211], v207 offset:40960
	s_waitcnt lgkmcnt(0)
	v_mfma_f32_32x32x16_bf16 v[130:145], v[208:211], v[232:235], v[130:145]
	s_cbranch_scc1 .LBB0_724
	s_mov_b64 s[6:7], -1
	s_cbranch_execnz .LBB0_705

.LBB0_709:
	s_cmp_lt_u32 s40, 31
	s_cselect_b32 s2, 0, 0xffffffe0
	s_cselect_b32 s8, s12, s13
	s_add_i32 s2, s2, s40
	s_lshl_b32 s2, s2, 6
	s_add_i32 s2, s2, s8
	s_add_i32 s2, s2, 64
	s_mul_hi_u32 s9, s2, 0x1600
	s_mulk_i32 s2, 0x1600
	s_add_u32 s8, s36, s2
	s_addc_u32 s9, s38, s9
	s_lshl_b32 s2, s3, 14
	s_xor_b32 s3, s2, 0x4000
	s_add_u32 s10, s8, 0x1200
	s_addc_u32 s11, s9, 0
	s_add_u32 s8, s8, s26
	s_addc_u32 s9, s9, s27
	s_add_i32 s3, s39, s3
	s_add_i32 m0, s3, 0x8000
	s_nop 0
	global_load_lds_dwordx4 v0, s[8:9]
	s_mov_b32 m0, s3
	s_nop 0
	global_load_lds_dwordx4 v196, s[10:11]
	s_add_i32 m0, s3, 0x8400
	s_nop 0
	global_load_lds_dwordx4 v198, s[8:9]
	s_add_i32 m0, s3, 0x400
	s_nop 0
	global_load_lds_dwordx4 v200, s[10:11]
	s_andn2_b64 vcc, exec, s[6:7]
	s_add_i32 s3, s2, 0
	s_sub_i32 s98, s3, s15
	s_cbranch_vccz .LBB0_702

.LBB0_712:
	s_andn2_b64 vcc, exec, s[10:11]
	s_cbranch_vccnz .LBB0_719
	s_nop 2
	v_add_u32_e32 v130, s98, v225
	ds_read_b128 v[130:133], v130 offset:32768
	ds_read_b128 v[134:137], v225
	v_add_u32_e32 v138, v206, v216
	v_add_u32_e32 v207, s98, v226
	s_andn2_b64 vcc, exec, s[8:9]
	s_waitcnt lgkmcnt(0)
	v_mfma_f32_32x32x16_bf16 v[146:161], v[130:133], v[134:137], 0
	ds_read_b128 v[130:133], v138 offset:40960
	ds_read_b128 v[208:211], v207 offset:32768
	ds_read_b128 v[232:235], v226
	v_add_u32_e32 v207, v206, v217
	s_waitcnt lgkmcnt(0)
	v_mfma_f32_32x32x16_bf16 v[146:161], v[208:211], v[232:235], v[146:161]
	ds_read_b128 v[208:211], v207 offset:40960
	v_add_u32_e32 v207, s98, v227
	v_mfma_f32_32x32x16_bf16 v[130:145], v[130:133], v[134:137], 0
	s_waitcnt lgkmcnt(0)
	v_mfma_f32_32x32x16_bf16 v[130:145], v[208:211], v[232:235], v[130:145]
	ds_read_b128 v[208:211], v207 offset:32768
	ds_read_b128 v[232:235], v227
	v_add_u32_e32 v207, v206, v218
	v_add_u32_e32 v206, v206, v219
	s_waitcnt lgkmcnt(0)
	v_mfma_f32_32x32x16_bf16 v[146:161], v[208:211], v[232:235], v[146:161]
	ds_read_b128 v[208:211], v207 offset:40960
	v_add_u32_e32 v207, s98, v228
	s_waitcnt lgkmcnt(0)
	v_mfma_f32_32x32x16_bf16 v[130:145], v[208:211], v[232:235], v[130:145]
	ds_read_b128 v[208:211], v207 offset:32768
	ds_read_b128 v[232:235], v228
	s_waitcnt lgkmcnt(0)
	v_mfma_f32_32x32x16_bf16 v[146:161], v[208:211], v[232:235], v[146:161]
	ds_read_b128 v[206:209], v206 offset:40960
	s_waitcnt lgkmcnt(0)
	v_mfma_f32_32x32x16_bf16 v[130:145], v[206:209], v[232:235], v[130:145]
	s_cbranch_vccnz .LBB0_725
	s_mov_b64 s[6:7], -1
	s_cbranch_execnz .LBB0_716

.LBB0_720:
	v_add_u32_e32 v130, s98, v221
	ds_read_b128 v[130:133], v130 offset:32768
	v_add_u32_e32 v178, s3, v212
	v_add_u32_e32 v134, v178, v220
	ds_read_b128 v[134:137], v134 offset:40960
	ds_read_b128 v[138:141], v221
	v_add_u32_e32 v162, s98, v222
	ds_read_b128 v[162:165], v162 offset:32768
	v_add_u32_e32 v166, v178, v213
	s_waitcnt lgkmcnt(0)
	v_mfma_f32_32x32x16_bf16 v[146:161], v[130:133], v[138:141], 0
	ds_read_b128 v[166:169], v166 offset:40960
	ds_read_b128 v[170:173], v222
	s_cmp_lg_u32 s40, 0
	s_cselect_b64 s[8:9], -1, 0
	s_or_b64 vcc, s[4:5], s[8:9]
	v_cndmask_b32_e32 v230, v253, v230, vcc
	v_mfma_f32_32x32x16_bf16 v[130:145], v[134:137], v[138:141], 0
	s_mov_b32 s4, 0x41000000
	v_mov_b32_e32 v206, 1.0
	s_waitcnt lgkmcnt(0)
	v_mfma_f32_32x32x16_bf16 v[146:161], v[162:165], v[170:173], v[146:161]
	v_add_u32_e32 v162, s98, v223
	ds_read_b128 v[162:165], v162 offset:32768
	v_mfma_f32_32x32x16_bf16 v[130:145], v[166:169], v[170:173], v[130:145]
	v_add_u32_e32 v166, v178, v214
	ds_read_b128 v[166:169], v166 offset:40960
	ds_read_b128 v[170:173], v223
	s_waitcnt lgkmcnt(0)
	v_mfma_f32_32x32x16_bf16 v[146:161], v[162:165], v[170:173], v[146:161]
	v_add_u32_e32 v162, s98, v224
	ds_read_b128 v[162:165], v162 offset:32768
	v_mfma_f32_32x32x16_bf16 v[130:145], v[166:169], v[170:173], v[130:145]
	v_add_u32_e32 v166, v178, v215
	ds_read_b128 v[166:169], v166 offset:40960
	ds_read_b128 v[170:173], v224
	s_waitcnt lgkmcnt(0)
	v_mfma_f32_32x32x16_bf16 v[146:161], v[162:165], v[170:173], v[146:161]
	v_mfma_f32_32x32x16_bf16 v[130:145], v[166:169], v[170:173], v[130:145]
	s_nop 10
	v_max_f32_e32 v162, v147, v147
	v_max_f32_e32 v163, v146, v146
	v_max_f32_e32 v162, v163, v162
	v_max3_f32 v162, v162, v148, v149
	v_max3_f32 v162, v162, v150, v151
	v_max3_f32 v162, v162, v152, v153
	v_max3_f32 v162, v162, v154, v155
	v_max3_f32 v162, v162, v156, v157
	v_max3_f32 v162, v162, v158, v159
	v_max3_f32 v162, v162, v160, v161
	v_max3_f32 v162, v162, v130, v131
	v_max3_f32 v162, v162, v132, v133
	v_max3_f32 v162, v162, v134, v135
	v_max3_f32 v162, v162, v136, v137
	v_max3_f32 v162, v162, v138, v139
	v_max3_f32 v162, v162, v140, v141
	v_max3_f32 v162, v162, v142, v143
	v_max3_f32 v162, v162, v144, v145
	v_mov_b32_e32 v163, v162
	s_nop 1
	v_permlane32_swap_b32_e32 v162, v163
	v_max_f32_e32 v163, v163, v163
	v_max_f32_e32 v162, v162, v162
	v_max_f32_e32 v162, v162, v163
	v_sub_f32_e32 v163, v162, v230
	v_cmp_ge_f32_e64 s[4:5], s4, v163
	s_cmp_eq_u64 s[4:5], exec
	s_cbranch_scc0 .LBB0_726
.LBB0_721:
	v_sub_f32_e32 v146, v146, v230
	v_exp_f32_e32 v146, v146
	v_sub_f32_e32 v147, v147, v230
	v_exp_f32_e32 v147, v147
	v_sub_f32_e32 v148, v148, v230
	v_exp_f32_e32 v148, v148
	v_sub_f32_e32 v149, v149, v230
	v_exp_f32_e32 v149, v149
	v_sub_f32_e32 v150, v150, v230
	v_add_f32_e32 v162, 0, v146
	v_exp_f32_e32 v150, v150
	v_sub_f32_e32 v151, v151, v230
	v_add_f32_e32 v162, v147, v162
	v_exp_f32_e32 v151, v151
	v_sub_f32_e32 v152, v152, v230
	v_add_f32_e32 v162, v148, v162
	v_exp_f32_e32 v152, v152
	v_sub_f32_e32 v153, v153, v230
	v_add_f32_e32 v162, v149, v162
	v_exp_f32_e32 v153, v153
	v_sub_f32_e32 v154, v154, v230
	v_add_f32_e32 v162, v150, v162
	v_exp_f32_e32 v154, v154
	v_sub_f32_e32 v155, v155, v230
	v_add_f32_e32 v162, v151, v162
	v_exp_f32_e32 v155, v155
	v_sub_f32_e32 v156, v156, v230
	v_add_f32_e32 v162, v152, v162
	v_exp_f32_e32 v156, v156
	v_sub_f32_e32 v157, v157, v230
	v_add_f32_e32 v162, v153, v162
	v_exp_f32_e32 v157, v157
	v_sub_f32_e32 v158, v158, v230
	v_add_f32_e32 v162, v154, v162
	v_exp_f32_e32 v158, v158
	v_sub_f32_e32 v159, v159, v230
	v_add_f32_e32 v162, v155, v162
	v_exp_f32_e32 v159, v159
	v_sub_f32_e32 v160, v160, v230
	v_add_f32_e32 v162, v156, v162
	v_exp_f32_e32 v160, v160
	v_sub_f32_e32 v161, v161, v230
	v_add_f32_e32 v162, v157, v162
	v_exp_f32_e32 v161, v161
	v_sub_f32_e32 v130, v130, v230
	v_add_f32_e32 v162, v158, v162
	v_exp_f32_e32 v130, v130
	v_sub_f32_e32 v131, v131, v230
	v_add_f32_e32 v162, v159, v162
	v_exp_f32_e32 v131, v131
	v_sub_f32_e32 v132, v132, v230
	v_add_f32_e32 v162, v160, v162
	v_exp_f32_e32 v132, v132
	v_sub_f32_e32 v133, v133, v230
	v_add_f32_e32 v162, v161, v162
	v_exp_f32_e32 v133, v133
	v_sub_f32_e32 v134, v134, v230
	v_add_f32_e32 v162, v130, v162
	v_exp_f32_e32 v134, v134
	v_sub_f32_e32 v135, v135, v230
	v_add_f32_e32 v162, v131, v162
	v_exp_f32_e32 v135, v135
	v_sub_f32_e32 v136, v136, v230
	v_add_f32_e32 v162, v132, v162
	v_exp_f32_e32 v136, v136
	v_sub_f32_e32 v137, v137, v230
	v_add_f32_e32 v162, v133, v162
	v_exp_f32_e32 v137, v137
	v_sub_f32_e32 v138, v138, v230
	v_add_f32_e32 v162, v134, v162
	v_exp_f32_e32 v138, v138
	v_sub_f32_e32 v139, v139, v230
	v_add_f32_e32 v162, v135, v162
	v_exp_f32_e32 v139, v139
	v_sub_f32_e32 v140, v140, v230
	v_add_f32_e32 v162, v136, v162
	v_exp_f32_e32 v140, v140
	v_sub_f32_e32 v141, v141, v230
	v_add_f32_e32 v162, v137, v162
	v_exp_f32_e32 v141, v141
	v_sub_f32_e32 v142, v142, v230
	v_add_f32_e32 v162, v138, v162
	v_exp_f32_e32 v142, v142
	v_sub_f32_e32 v143, v143, v230
	v_add_f32_e32 v162, v139, v162
	v_exp_f32_e32 v143, v143
	v_sub_f32_e32 v144, v144, v230
	v_add_f32_e32 v162, v140, v162
	v_exp_f32_e32 v144, v144
	v_sub_f32_e32 v145, v145, v230
	v_add_f32_e32 v162, v141, v162
	v_exp_f32_e32 v145, v145
	v_add_f32_e32 v162, v142, v162
	v_add_f32_e32 v162, v143, v162
	v_add_f32_e32 v162, v144, v162
	v_add_f32_e32 v208, v145, v162
	v_cvt_pk_bf16_f32 v162, v146, v147
	v_cvt_pk_bf16_f32 v163, v148, v149
	v_cvt_pk_bf16_f32 v164, v150, v151
	v_cvt_pk_bf16_f32 v165, v152, v153
	v_cvt_pk_bf16_f32 v166, v154, v155
	v_cvt_pk_bf16_f32 v167, v156, v157
	v_cvt_pk_bf16_f32 v168, v158, v159
	v_cvt_pk_bf16_f32 v169, v160, v161
	v_cvt_pk_bf16_f32 v170, v130, v131
	v_cvt_pk_bf16_f32 v171, v132, v133
	v_cvt_pk_bf16_f32 v172, v134, v135
	v_add_u32_e32 v130, s98, v225
	v_add_u32_e32 v134, v178, v216
	v_cvt_pk_bf16_f32 v173, v136, v137
	v_cvt_pk_bf16_f32 v174, v138, v139
	v_cvt_pk_bf16_f32 v175, v140, v141
	v_cvt_pk_bf16_f32 v176, v142, v143
	v_cvt_pk_bf16_f32 v177, v144, v145
	ds_read_b128 v[130:133], v130 offset:32768
	ds_read_b128 v[134:137], v134 offset:40960
	ds_read_b128 v[138:141], v225
	v_add_u32_e32 v180, s98, v226
	v_add_u32_e32 v184, v178, v217
	ds_read_b128 v[180:183], v180 offset:32768
	ds_read_b128 v[184:187], v184 offset:40960
	s_waitcnt lgkmcnt(0)
	v_mfma_f32_32x32x16_bf16 v[146:161], v[130:133], v[138:141], 0
	ds_read_b128 v[188:191], v226
	v_cndmask_b32_e32 v179, v253, v231, vcc
	v_mov_b32_e32 v210, v208
	s_nop 1
	v_permlane32_swap_b32_e32 v208, v210
	v_mfma_f32_32x32x16_bf16 v[130:145], v[134:137], v[138:141], 0
	s_waitcnt lgkmcnt(0)
	v_mfma_f32_32x32x16_bf16 v[146:161], v[180:183], v[188:191], v[146:161]
	v_add_u32_e32 v180, s98, v227
	ds_read_b128 v[180:183], v180 offset:32768
	v_mfma_f32_32x32x16_bf16 v[130:145], v[184:187], v[188:191], v[130:145]
	v_add_u32_e32 v184, v178, v218
	ds_read_b128 v[184:187], v184 offset:40960
	ds_read_b128 v[188:191], v227
	v_add_u32_e32 v178, v178, v219
	s_waitcnt lgkmcnt(0)
	v_mfma_f32_32x32x16_bf16 v[130:145], v[184:187], v[188:191], v[130:145]
	ds_read_b128 v[184:187], v178 offset:40960
	v_mfma_f32_32x32x16_bf16 v[146:161], v[180:183], v[188:191], v[146:161]
	v_add_u32_e32 v180, s98, v228
	ds_read_b128 v[180:183], v180 offset:32768
	ds_read_b128 v[188:191], v228
	s_mov_b32 s3, 0x41000000
	s_waitcnt lgkmcnt(0)
	v_mfma_f32_32x32x16_bf16 v[146:161], v[180:183], v[188:191], v[146:161]
	v_mfma_f32_32x32x16_bf16 v[130:145], v[184:187], v[188:191], v[130:145]
	s_nop 10
	v_max_f32_e32 v178, v147, v147
	v_max_f32_e32 v180, v146, v146
	v_max_f32_e32 v178, v180, v178
	v_max3_f32 v178, v178, v148, v149
	v_max3_f32 v178, v178, v150, v151
	v_max3_f32 v178, v178, v152, v153
	v_max3_f32 v178, v178, v154, v155
	v_max3_f32 v178, v178, v156, v157
	v_max3_f32 v178, v178, v158, v159
	v_max3_f32 v178, v178, v160, v161
	v_max3_f32 v178, v178, v130, v131
	v_max3_f32 v178, v178, v132, v133
	v_max3_f32 v178, v178, v134, v135
	v_max3_f32 v178, v178, v136, v137
	v_max3_f32 v178, v178, v138, v139
	v_max3_f32 v178, v178, v140, v141
	v_max3_f32 v178, v178, v142, v143
	v_max3_f32 v178, v178, v144, v145
	v_mov_b32_e32 v180, v178
	s_nop 1
	v_permlane32_swap_b32_e32 v178, v180
	v_max_f32_e32 v180, v180, v180
	v_max_f32_e32 v178, v178, v178
	v_max_f32_e32 v178, v178, v180
	v_sub_f32_e32 v180, v178, v179
	v_cmp_ge_f32_e32 vcc, s3, v180
	s_cmp_eq_u64 vcc, exec
	v_max_f32_e32 v180, v179, v179
	s_cselect_b64 vcc, -1, 0
	v_max_f32_e32 v178, v180, v178
	v_cndmask_b32_e32 v231, v178, v179, vcc
	v_sub_f32_e32 v146, v146, v231
	v_exp_f32_e32 v146, v146
	v_sub_f32_e32 v147, v147, v231
	v_exp_f32_e32 v147, v147
	v_sub_f32_e32 v148, v148, v231
	v_exp_f32_e32 v148, v148
	v_sub_f32_e32 v149, v149, v231
	v_exp_f32_e32 v149, v149
	v_sub_f32_e32 v150, v150, v231
	v_sub_f32_e32 v180, v179, v178
	v_add_f32_e32 v178, 0, v146
	v_exp_f32_e32 v150, v150
	v_sub_f32_e32 v151, v151, v231
	v_add_f32_e32 v178, v147, v178
	v_exp_f32_e32 v151, v151
	v_sub_f32_e32 v152, v152, v231
	v_add_f32_e32 v178, v148, v178
	v_exp_f32_e32 v152, v152
	v_sub_f32_e32 v153, v153, v231
	v_add_f32_e32 v178, v149, v178
	v_exp_f32_e32 v153, v153
	v_sub_f32_e32 v154, v154, v231
	v_add_f32_e32 v178, v150, v178
	v_exp_f32_e32 v154, v154
	v_sub_f32_e32 v155, v155, v231
	v_add_f32_e32 v178, v151, v178
	v_exp_f32_e32 v155, v155
	v_sub_f32_e32 v156, v156, v231
	v_add_f32_e32 v178, v152, v178
	v_exp_f32_e32 v156, v156
	v_sub_f32_e32 v157, v157, v231
	v_add_f32_e32 v178, v153, v178
	v_exp_f32_e32 v157, v157
	v_sub_f32_e32 v158, v158, v231
	v_add_f32_e32 v178, v154, v178
	v_exp_f32_e32 v158, v158
	v_sub_f32_e32 v159, v159, v231
	v_add_f32_e32 v178, v155, v178
	v_exp_f32_e32 v159, v159
	v_sub_f32_e32 v160, v160, v231
	v_add_f32_e32 v178, v156, v178
	v_exp_f32_e32 v160, v160
	v_sub_f32_e32 v161, v161, v231
	v_add_f32_e32 v178, v157, v178
	v_exp_f32_e32 v161, v161
	v_sub_f32_e32 v130, v130, v231
	v_add_f32_e32 v178, v158, v178
	v_exp_f32_e32 v130, v130
	v_sub_f32_e32 v131, v131, v231
	v_add_f32_e32 v178, v159, v178
	v_exp_f32_e32 v131, v131
	v_sub_f32_e32 v132, v132, v231
	v_add_f32_e32 v178, v160, v178
	v_exp_f32_e32 v132, v132
	v_sub_f32_e32 v133, v133, v231
	v_add_f32_e32 v178, v161, v178
	v_exp_f32_e32 v133, v133
	v_sub_f32_e32 v134, v134, v231
	v_add_f32_e32 v178, v130, v178
	v_exp_f32_e32 v134, v134
	v_sub_f32_e32 v135, v135, v231
	v_add_f32_e32 v178, v131, v178
	v_exp_f32_e32 v135, v135
	v_sub_f32_e32 v136, v136, v231
	v_add_f32_e32 v178, v132, v178
	v_exp_f32_e32 v136, v136
	v_sub_f32_e32 v137, v137, v231
	v_add_f32_e32 v178, v133, v178
	v_exp_f32_e32 v137, v137
	v_sub_f32_e32 v138, v138, v231
	v_add_f32_e32 v178, v134, v178
	v_exp_f32_e32 v138, v138
	v_sub_f32_e32 v139, v139, v231
	v_add_f32_e32 v178, v135, v178
	v_exp_f32_e32 v139, v139
	v_sub_f32_e32 v140, v140, v231
	v_add_f32_e32 v178, v136, v178
	v_exp_f32_e32 v140, v140
	v_sub_f32_e32 v141, v141, v231
	v_add_f32_e32 v178, v137, v178
	v_exp_f32_e32 v141, v141
	v_sub_f32_e32 v142, v142, v231
	v_add_f32_e32 v178, v138, v178
	v_exp_f32_e32 v142, v142
	v_sub_f32_e32 v143, v143, v231
	v_add_f32_e32 v178, v139, v178
	v_exp_f32_e32 v143, v143
	v_sub_f32_e32 v144, v144, v231
	v_exp_f32_e32 v180, v180
	v_add_f32_e32 v178, v140, v178
	v_exp_f32_e32 v144, v144
	v_sub_f32_e32 v145, v145, v231
	v_add_f32_e32 v178, v141, v178
	v_exp_f32_e32 v145, v145
	v_add_f32_e32 v178, v142, v178
	v_add_f32_e32 v178, v143, v178
	v_cndmask_b32_e64 v207, v180, 1.0, vcc
	v_add_f32_e32 v178, v144, v178
	v_add_f32_e32 v209, v145, v178
	v_cvt_pk_bf16_f32 v178, v146, v147
	v_cvt_pk_bf16_f32 v179, v148, v149
	v_cvt_pk_bf16_f32 v180, v150, v151
	v_cvt_pk_bf16_f32 v181, v152, v153
	v_cvt_pk_bf16_f32 v182, v154, v155
	v_cvt_pk_bf16_f32 v183, v156, v157
	v_cvt_pk_bf16_f32 v184, v158, v159
	v_cvt_pk_bf16_f32 v185, v160, v161
	v_cvt_pk_bf16_f32 v186, v130, v131
	v_max_f32_e32 v130, v207, v207
	v_max_f32_e32 v131, v206, v206
	v_mov_b32_e32 v211, v209
	v_min_f32_e32 v130, v131, v130
	s_nop 0
	v_permlane32_swap_b32_e32 v209, v211
	v_cmp_gt_f32_e32 vcc, 1.0, v130
	v_cvt_pk_bf16_f32 v187, v132, v133
	v_cvt_pk_bf16_f32 v188, v134, v135
	v_cvt_pk_bf16_f32 v189, v136, v137
	v_cvt_pk_bf16_f32 v190, v138, v139
	v_cvt_pk_bf16_f32 v191, v140, v141
	v_cvt_pk_bf16_f32 v192, v142, v143
	v_cvt_pk_bf16_f32 v193, v144, v145
	s_cbranch_vccz .LBB0_697
	v_mbcnt_lo_u32_b32 v130, -1, 0
	v_mbcnt_hi_u32_b32 v130, -1, v130
	s_nop 0
	v_cmp_gt_u32_e32 vcc, 32, v130
	s_and_saveexec_b64 s[4:5], vcc
	s_cbranch_execz .LBB0_696
	v_lshl_add_u32 v131, v130, 2, s14
	ds_write2_b32 v131, v206, v207 offset1:32
	s_branch .LBB0_696
